# RG-LRU pass B scan fetched up front with h written back afterwards; wave-local LDS fences between sub-block stages removed in both passes (LDS executes a wave's operations in order)
# baseline (speedup 1.0000x reference)
.LBB0_207:
	ds_read_b128 v[138:141], v180 offset:11008
	ds_read_b128 v[222:225], v180 offset:11152
	ds_read_b128 v[226:229], v180 offset:11296
	ds_read_b128 v[230:233], v180 offset:11440
	s_add_i32 s43, s43, 16
	s_cmpk_lg_i32 s43, 0x80
	s_waitcnt lgkmcnt(3)
	v_lshlrev_b32_e32 v124, 16, v138
	v_and_b32_e32 v125, 0xffff0000, v138
	v_lshlrev_b32_e32 v120, 16, v139
	v_and_b32_e32 v121, 0xffff0000, v139
	v_lshlrev_b32_e32 v126, 16, v140
	v_and_b32_e32 v127, 0xffff0000, v140
	v_lshlrev_b32_e32 v122, 16, v141
	v_and_b32_e32 v123, 0xffff0000, v141
	ds_read_b128 v[138:141], v180 offset:12160
	v_pk_fma_f32 v[128:129], v[6:7], v[120:121], v[22:23]
	v_pk_fma_f32 v[130:131], v[2:3], v[122:123], v[18:19]
	v_pk_fma_f32 v[124:125], v[4:5], v[124:125], v[20:21]
	v_pk_fma_f32 v[126:127], v[0:1], v[126:127], v[16:17]
	s_waitcnt lgkmcnt(3)
	v_lshlrev_b32_e32 v132, 16, v222
	v_and_b32_e32 v133, 0xffff0000, v222
	v_lshlrev_b32_e32 v120, 16, v223
	v_and_b32_e32 v121, 0xffff0000, v223
	v_lshlrev_b32_e32 v134, 16, v224
	v_and_b32_e32 v135, 0xffff0000, v224
	v_lshlrev_b32_e32 v122, 16, v225
	v_and_b32_e32 v123, 0xffff0000, v225
	ds_read_b128 v[222:225], v180 offset:12304
	v_pk_fma_f32 v[128:129], v[14:15], v[120:121], v[128:129]
	v_pk_fma_f32 v[130:131], v[10:11], v[122:123], v[130:131]
	v_pk_fma_f32 v[124:125], v[12:13], v[132:133], v[124:125]
	v_pk_fma_f32 v[126:127], v[8:9], v[134:135], v[126:127]
	s_waitcnt lgkmcnt(3)
	v_lshlrev_b32_e32 v132, 16, v226
	v_and_b32_e32 v133, 0xffff0000, v226
	v_lshlrev_b32_e32 v120, 16, v227
	v_and_b32_e32 v121, 0xffff0000, v227
	v_lshlrev_b32_e32 v134, 16, v228
	v_and_b32_e32 v135, 0xffff0000, v228
	v_lshlrev_b32_e32 v122, 16, v229
	v_and_b32_e32 v123, 0xffff0000, v229
	ds_read_b128 v[226:229], v180 offset:12448
	v_pk_fma_f32 v[124:125], v[24:25], v[132:133], v[124:125]
	v_pk_fma_f32 v[128:129], v[26:27], v[120:121], v[128:129]
	v_pk_fma_f32 v[132:133], v[28:29], v[134:135], v[126:127]
	v_pk_fma_f32 v[126:127], v[30:31], v[122:123], v[130:131]
	s_waitcnt lgkmcnt(3)
	v_lshlrev_b32_e32 v130, 16, v230
	v_and_b32_e32 v131, 0xffff0000, v230
	v_lshlrev_b32_e32 v120, 16, v231
	v_and_b32_e32 v121, 0xffff0000, v231
	v_lshlrev_b32_e32 v134, 16, v232
	v_and_b32_e32 v135, 0xffff0000, v232
	v_lshlrev_b32_e32 v136, 16, v233
	v_and_b32_e32 v137, 0xffff0000, v233
	ds_read_b128 v[230:233], v180 offset:12592
	v_pk_fma_f32 v[122:123], v[34:35], v[120:121], v[128:129]
	v_pk_fma_f32 v[120:121], v[32:33], v[130:131], v[124:125]
	v_pk_fma_f32 v[126:127], v[38:39], v[136:137], v[126:127]
	v_pk_fma_f32 v[124:125], v[36:37], v[134:135], v[132:133]
	ds_write_b128 v179, v[120:123] offset:2304
	ds_write_b128 v179, v[124:127] offset:2320
	v_cvt_pk_bf16_f32 v120, v120, v121
	v_cvt_pk_bf16_f32 v121, v122, v123
	v_cvt_pk_bf16_f32 v122, v124, v125
	v_cvt_pk_bf16_f32 v123, v126, v127
	ds_write_b128 v180, v[120:123]
	s_waitcnt lgkmcnt(6)
	v_lshlrev_b32_e32 v124, 16, v138
	v_and_b32_e32 v125, 0xffff0000, v138
	v_lshlrev_b32_e32 v120, 16, v139
	v_and_b32_e32 v121, 0xffff0000, v139
	v_lshlrev_b32_e32 v126, 16, v140
	v_and_b32_e32 v127, 0xffff0000, v140
	v_lshlrev_b32_e32 v122, 16, v141
	v_and_b32_e32 v123, 0xffff0000, v141
	v_pk_fma_f32 v[128:129], v[6:7], v[120:121], v[22:23]
	v_pk_fma_f32 v[130:131], v[2:3], v[122:123], v[18:19]
	v_pk_fma_f32 v[124:125], v[4:5], v[124:125], v[20:21]
	v_pk_fma_f32 v[126:127], v[0:1], v[126:127], v[16:17]
	s_waitcnt lgkmcnt(5)
	v_lshlrev_b32_e32 v132, 16, v222
	v_and_b32_e32 v133, 0xffff0000, v222
	v_lshlrev_b32_e32 v120, 16, v223
	v_and_b32_e32 v121, 0xffff0000, v223
	v_lshlrev_b32_e32 v134, 16, v224
	v_and_b32_e32 v135, 0xffff0000, v224
	v_lshlrev_b32_e32 v122, 16, v225
	v_and_b32_e32 v123, 0xffff0000, v225
	v_pk_fma_f32 v[128:129], v[14:15], v[120:121], v[128:129]
	v_pk_fma_f32 v[130:131], v[10:11], v[122:123], v[130:131]
	v_pk_fma_f32 v[124:125], v[12:13], v[132:133], v[124:125]
	v_pk_fma_f32 v[126:127], v[8:9], v[134:135], v[126:127]
	s_waitcnt lgkmcnt(4)
	v_lshlrev_b32_e32 v132, 16, v226
	v_and_b32_e32 v133, 0xffff0000, v226
	v_lshlrev_b32_e32 v120, 16, v227
	v_and_b32_e32 v121, 0xffff0000, v227
	v_lshlrev_b32_e32 v134, 16, v228
	v_and_b32_e32 v135, 0xffff0000, v228
	v_lshlrev_b32_e32 v122, 16, v229
	v_and_b32_e32 v123, 0xffff0000, v229
	v_pk_fma_f32 v[124:125], v[24:25], v[132:133], v[124:125]
	v_pk_fma_f32 v[128:129], v[26:27], v[120:121], v[128:129]
	v_pk_fma_f32 v[132:133], v[28:29], v[134:135], v[126:127]
	v_pk_fma_f32 v[126:127], v[30:31], v[122:123], v[130:131]
	s_waitcnt lgkmcnt(3)
	v_lshlrev_b32_e32 v130, 16, v230
	v_and_b32_e32 v131, 0xffff0000, v230
	v_lshlrev_b32_e32 v120, 16, v231
	v_and_b32_e32 v121, 0xffff0000, v231
	v_lshlrev_b32_e32 v134, 16, v232
	v_and_b32_e32 v135, 0xffff0000, v232
	v_lshlrev_b32_e32 v136, 16, v233
	v_and_b32_e32 v137, 0xffff0000, v233
	v_pk_fma_f32 v[122:123], v[34:35], v[120:121], v[128:129]
	v_pk_fma_f32 v[120:121], v[32:33], v[130:131], v[124:125]
	v_pk_fma_f32 v[126:127], v[38:39], v[136:137], v[126:127]
	v_pk_fma_f32 v[124:125], v[36:37], v[134:135], v[132:133]
	ds_write_b128 v179, v[120:123] offset:4480
	ds_write_b128 v179, v[124:127] offset:4496
	v_cvt_pk_bf16_f32 v120, v120, v121
	v_cvt_pk_bf16_f32 v121, v122, v123
	v_cvt_pk_bf16_f32 v122, v124, v125
	v_cvt_pk_bf16_f32 v123, v126, v127
	ds_write_b128 v180, v[120:123] offset:1152
	s_mov_b32 s0, 0x37d00d01
	s_mov_b32 s1, 0x37d00d01
	s_mov_b32 s80, 0x3ab60b61
	s_mov_b32 s81, 0x3ab60b61
	s_mov_b32 s82, 0x3c088889
	s_mov_b32 s83, 0x3c088889
	s_mov_b32 s84, 0x3d2aaaab
	s_mov_b32 s85, 0x3d2aaaab
	ds_read_b128 v[120:123], v173
	ds_read_b128 v[222:225], v173 offset:64
	v_mov_b32_e32 v168, 1.0
	v_mov_b32_e32 v232, 0xbfb8aa3b
	v_add_u32_e32 v233, 2304, v175
	s_waitcnt lgkmcnt(0)
	v_mfma_f32_16x16x32_bf16 v[128:131], v[120:123], v[40:43], 0
	v_mfma_f32_16x16x32_bf16 v[132:135], v[120:123], v[72:75], 0
	v_mfma_f32_16x16x32_bf16 v[128:131], v[222:225], v[44:47], v[128:131]
	v_mfma_f32_16x16x32_bf16 v[132:135], v[222:225], v[76:79], v[132:135]
	v_mfma_f32_16x16x32_bf16 v[136:139], v[120:123], v[48:51], 0
	v_mfma_f32_16x16x32_bf16 v[140:143], v[120:123], v[80:83], 0
	v_mfma_f32_16x16x32_bf16 v[136:139], v[222:225], v[52:55], v[136:139]
	v_mfma_f32_16x16x32_bf16 v[140:143], v[222:225], v[84:87], v[140:143]
	s_nop 7
	ds_read2_b32 v[230:231], v233 offset0:0 offset1:68
	v_add_f32_e64 v124, v128, v161
	v_add_f32_e64 v125, v129, v161
	v_add_f32_e64 v126, v132, v163
	v_add_f32_e64 v127, v133, v163
	v_pk_mul_f32 v[124:125], v[124:125], v[232:233] op_sel_hi:[1,0]
	v_pk_mul_f32 v[126:127], v[126:127], v[232:233] op_sel_hi:[1,0]
	v_exp_f32_e32 v124, v124
	v_exp_f32_e32 v125, v125
	v_exp_f32_e32 v126, v126
	v_exp_f32_e32 v127, v127
	v_pk_add_f32 v[124:125], v[124:125], v[168:169] op_sel_hi:[1,0]
	v_pk_add_f32 v[126:127], v[126:127], v[168:169] op_sel_hi:[1,0]
	v_rcp_f32_e32 v124, v124
	v_rcp_f32_e32 v125, v125
	v_rcp_f32_e32 v126, v126
	v_rcp_f32_e32 v127, v127
	v_pk_mul_f32 v[170:171], v[124:125], v[98:99] op_sel_hi:[1,0]
	v_mul_f32_e32 v226, 0x3fb8aa3b, v170
	v_mul_f32_e32 v227, 0x3fb8aa3b, v171
	v_pk_add_f32 v[170:171], v[170:171], v[170:171]
	v_exp_f32_e32 v226, v226
	v_exp_f32_e32 v227, v227
	v_pk_fma_f32 v[228:229], v[170:171], s[0:1], v[198:199] op_sel_hi:[1,1,0]
	v_pk_fma_f32 v[228:229], v[170:171], v[228:229], s[80:81]
	v_pk_fma_f32 v[228:229], v[170:171], v[228:229], s[82:83]
	v_pk_fma_f32 v[228:229], v[170:171], v[228:229], s[84:85]
	v_fmaak_f32 v228, v170, v228, 0x3e2aaaab
	v_fmaak_f32 v229, v171, v229, 0x3e2aaaab
	v_fma_f32 v228, v170, v228, 0.5
	v_fma_f32 v229, v171, v229, 0.5
	v_pk_fma_f32 v[228:229], v[170:171], v[228:229], v[168:169] op_sel_hi:[1,1,0]
	v_pk_mul_f32 v[228:229], v[170:171], v[228:229] neg_lo:[0,1] neg_hi:[0,1]
	v_max_f32_e32 v228, 0, v228
	v_max_f32_e32 v229, 0, v229
	v_sqrt_f32_e32 v228, v228
	v_sqrt_f32_e32 v229, v229
	ds_write_b32 v175, v226 offset:6656
	ds_write_b32 v175, v227 offset:6928
	v_pk_mul_f32 v[228:229], v[126:127], v[228:229]
	s_waitcnt lgkmcnt(2)
	v_pk_mul_f32 v[228:229], v[230:231], v[228:229]
	ds_write2_b32 v233, v228, v229 offset0:0 offset1:68
	ds_read2_b32 v[230:231], v233 offset0:136 offset1:204
	v_add_f32_e64 v124, v130, v161
	v_add_f32_e64 v125, v131, v161
	v_add_f32_e64 v126, v134, v163
	v_add_f32_e64 v127, v135, v163
	v_pk_mul_f32 v[124:125], v[124:125], v[232:233] op_sel_hi:[1,0]
	v_pk_mul_f32 v[126:127], v[126:127], v[232:233] op_sel_hi:[1,0]
	v_exp_f32_e32 v124, v124
	v_exp_f32_e32 v125, v125
	v_exp_f32_e32 v126, v126
	v_exp_f32_e32 v127, v127
	v_pk_add_f32 v[124:125], v[124:125], v[168:169] op_sel_hi:[1,0]
	v_pk_add_f32 v[126:127], v[126:127], v[168:169] op_sel_hi:[1,0]
	v_rcp_f32_e32 v124, v124
	v_rcp_f32_e32 v125, v125
	v_rcp_f32_e32 v126, v126
	v_rcp_f32_e32 v127, v127
	v_pk_mul_f32 v[170:171], v[124:125], v[98:99] op_sel_hi:[1,0]
	v_mul_f32_e32 v226, 0x3fb8aa3b, v170
	v_mul_f32_e32 v227, 0x3fb8aa3b, v171
	v_pk_add_f32 v[170:171], v[170:171], v[170:171]
	v_exp_f32_e32 v226, v226
	v_exp_f32_e32 v227, v227
	v_pk_fma_f32 v[228:229], v[170:171], s[0:1], v[198:199] op_sel_hi:[1,1,0]
	v_pk_fma_f32 v[228:229], v[170:171], v[228:229], s[80:81]
	v_pk_fma_f32 v[228:229], v[170:171], v[228:229], s[82:83]
	v_pk_fma_f32 v[228:229], v[170:171], v[228:229], s[84:85]
	v_fmaak_f32 v228, v170, v228, 0x3e2aaaab
	v_fmaak_f32 v229, v171, v229, 0x3e2aaaab
	v_fma_f32 v228, v170, v228, 0.5
	v_fma_f32 v229, v171, v229, 0.5
	v_pk_fma_f32 v[228:229], v[170:171], v[228:229], v[168:169] op_sel_hi:[1,1,0]
	v_pk_mul_f32 v[228:229], v[170:171], v[228:229] neg_lo:[0,1] neg_hi:[0,1]
	v_max_f32_e32 v228, 0, v228
	v_max_f32_e32 v229, 0, v229
	v_sqrt_f32_e32 v228, v228
	v_sqrt_f32_e32 v229, v229
	ds_write_b32 v175, v226 offset:7200
	ds_write_b32 v175, v227 offset:7472
	v_pk_mul_f32 v[228:229], v[126:127], v[228:229]
	s_waitcnt lgkmcnt(2)
	v_pk_mul_f32 v[228:229], v[230:231], v[228:229]
	ds_write2_b32 v233, v228, v229 offset0:136 offset1:204
	v_mfma_f32_16x16x32_bf16 v[128:131], v[120:123], v[56:59], 0
	v_mfma_f32_16x16x32_bf16 v[132:135], v[120:123], v[88:91], 0
	v_mfma_f32_16x16x32_bf16 v[128:131], v[222:225], v[60:63], v[128:131]
	v_mfma_f32_16x16x32_bf16 v[132:135], v[222:225], v[92:95], v[132:135]
	ds_read2_b32 v[230:231], v233 offset0:16 offset1:84
	v_add_f32_e64 v124, v136, v181
	v_add_f32_e64 v125, v137, v181
	v_pk_add_f32 v[126:127], v[140:141], v[188:189] op_sel_hi:[1,0]
	v_pk_mul_f32 v[124:125], v[124:125], v[232:233] op_sel_hi:[1,0]
	v_pk_mul_f32 v[126:127], v[126:127], v[232:233] op_sel_hi:[1,0]
	v_exp_f32_e32 v124, v124
	v_exp_f32_e32 v125, v125
	v_exp_f32_e32 v126, v126
	v_exp_f32_e32 v127, v127
	v_pk_add_f32 v[124:125], v[124:125], v[168:169] op_sel_hi:[1,0]
	v_pk_add_f32 v[126:127], v[126:127], v[168:169] op_sel_hi:[1,0]
	v_rcp_f32_e32 v124, v124
	v_rcp_f32_e32 v125, v125
	v_rcp_f32_e32 v126, v126
	v_rcp_f32_e32 v127, v127
	v_mul_f32_e64 v170, v124, v193
	v_mul_f32_e64 v171, v125, v193
	v_mul_f32_e32 v226, 0x3fb8aa3b, v170
	v_mul_f32_e32 v227, 0x3fb8aa3b, v171
	v_pk_add_f32 v[170:171], v[170:171], v[170:171]
	v_exp_f32_e32 v226, v226
	v_exp_f32_e32 v227, v227
	v_pk_fma_f32 v[228:229], v[170:171], s[0:1], v[198:199] op_sel_hi:[1,1,0]
	v_pk_fma_f32 v[228:229], v[170:171], v[228:229], s[80:81]
	v_pk_fma_f32 v[228:229], v[170:171], v[228:229], s[82:83]
	v_pk_fma_f32 v[228:229], v[170:171], v[228:229], s[84:85]
	v_fmaak_f32 v228, v170, v228, 0x3e2aaaab
	v_fmaak_f32 v229, v171, v229, 0x3e2aaaab
	v_fma_f32 v228, v170, v228, 0.5
	v_fma_f32 v229, v171, v229, 0.5
	v_pk_fma_f32 v[228:229], v[170:171], v[228:229], v[168:169] op_sel_hi:[1,1,0]
	v_pk_mul_f32 v[228:229], v[170:171], v[228:229] neg_lo:[0,1] neg_hi:[0,1]
	v_max_f32_e32 v228, 0, v228
	v_max_f32_e32 v229, 0, v229
	v_sqrt_f32_e32 v228, v228
	v_sqrt_f32_e32 v229, v229
	ds_write_b32 v175, v226 offset:6720
	ds_write_b32 v175, v227 offset:6992
	v_pk_mul_f32 v[228:229], v[126:127], v[228:229]
	s_waitcnt lgkmcnt(2)
	v_pk_mul_f32 v[228:229], v[230:231], v[228:229]
	ds_write2_b32 v233, v228, v229 offset0:16 offset1:84
	ds_read2_b32 v[230:231], v233 offset0:152 offset1:220
	v_add_f32_e64 v124, v138, v181
	v_add_f32_e64 v125, v139, v181
	v_pk_add_f32 v[126:127], v[142:143], v[188:189] op_sel_hi:[1,0]
	v_pk_mul_f32 v[124:125], v[124:125], v[232:233] op_sel_hi:[1,0]
	v_pk_mul_f32 v[126:127], v[126:127], v[232:233] op_sel_hi:[1,0]
	v_exp_f32_e32 v124, v124
	v_exp_f32_e32 v125, v125
	v_exp_f32_e32 v126, v126
	v_exp_f32_e32 v127, v127
	v_pk_add_f32 v[124:125], v[124:125], v[168:169] op_sel_hi:[1,0]
	v_pk_add_f32 v[126:127], v[126:127], v[168:169] op_sel_hi:[1,0]
	v_rcp_f32_e32 v124, v124
	v_rcp_f32_e32 v125, v125
	v_rcp_f32_e32 v126, v126
	v_rcp_f32_e32 v127, v127
	v_mul_f32_e64 v170, v124, v193
	v_mul_f32_e64 v171, v125, v193
	v_mul_f32_e32 v226, 0x3fb8aa3b, v170
	v_mul_f32_e32 v227, 0x3fb8aa3b, v171
	v_pk_add_f32 v[170:171], v[170:171], v[170:171]
	v_exp_f32_e32 v226, v226
	v_exp_f32_e32 v227, v227
	v_pk_fma_f32 v[228:229], v[170:171], s[0:1], v[198:199] op_sel_hi:[1,1,0]
	v_pk_fma_f32 v[228:229], v[170:171], v[228:229], s[80:81]
	v_pk_fma_f32 v[228:229], v[170:171], v[228:229], s[82:83]
	v_pk_fma_f32 v[228:229], v[170:171], v[228:229], s[84:85]
	v_fmaak_f32 v228, v170, v228, 0x3e2aaaab
	v_fmaak_f32 v229, v171, v229, 0x3e2aaaab
	v_fma_f32 v228, v170, v228, 0.5
	v_fma_f32 v229, v171, v229, 0.5
	v_pk_fma_f32 v[228:229], v[170:171], v[228:229], v[168:169] op_sel_hi:[1,1,0]
	v_pk_mul_f32 v[228:229], v[170:171], v[228:229] neg_lo:[0,1] neg_hi:[0,1]
	v_max_f32_e32 v228, 0, v228
	v_max_f32_e32 v229, 0, v229
	v_sqrt_f32_e32 v228, v228
	v_sqrt_f32_e32 v229, v229
	ds_write_b32 v175, v226 offset:7264
	ds_write_b32 v175, v227 offset:7536
	v_pk_mul_f32 v[228:229], v[126:127], v[228:229]
	s_waitcnt lgkmcnt(2)
	v_pk_mul_f32 v[228:229], v[230:231], v[228:229]
	ds_write2_b32 v233, v228, v229 offset0:152 offset1:220
	v_mfma_f32_16x16x32_bf16 v[136:139], v[120:123], v[64:67], 0
	v_mfma_f32_16x16x32_bf16 v[140:143], v[120:123], v[100:103], 0
	v_mfma_f32_16x16x32_bf16 v[136:139], v[222:225], v[68:71], v[136:139]
	v_mfma_f32_16x16x32_bf16 v[140:143], v[222:225], v[104:107], v[140:143]
	ds_read2_b32 v[230:231], v233 offset0:32 offset1:100
	v_add_f32_e64 v124, v128, v189
	v_add_f32_e64 v125, v129, v189
	v_pk_add_f32 v[126:127], v[132:133], v[190:191] op_sel_hi:[1,0]
	v_pk_mul_f32 v[124:125], v[124:125], v[232:233] op_sel_hi:[1,0]
	v_pk_mul_f32 v[126:127], v[126:127], v[232:233] op_sel_hi:[1,0]
	v_exp_f32_e32 v124, v124
	v_exp_f32_e32 v125, v125
	v_exp_f32_e32 v126, v126
	v_exp_f32_e32 v127, v127
	v_pk_add_f32 v[124:125], v[124:125], v[168:169] op_sel_hi:[1,0]
	v_pk_add_f32 v[126:127], v[126:127], v[168:169] op_sel_hi:[1,0]
	v_rcp_f32_e32 v124, v124
	v_rcp_f32_e32 v125, v125
	v_rcp_f32_e32 v126, v126
	v_rcp_f32_e32 v127, v127
	v_pk_mul_f32 v[170:171], v[124:125], v[220:221] op_sel_hi:[1,0]
	v_mul_f32_e32 v226, 0x3fb8aa3b, v170
	v_mul_f32_e32 v227, 0x3fb8aa3b, v171
	v_pk_add_f32 v[170:171], v[170:171], v[170:171]
	v_exp_f32_e32 v226, v226
	v_exp_f32_e32 v227, v227
	v_pk_fma_f32 v[228:229], v[170:171], s[0:1], v[198:199] op_sel_hi:[1,1,0]
	v_pk_fma_f32 v[228:229], v[170:171], v[228:229], s[80:81]
	v_pk_fma_f32 v[228:229], v[170:171], v[228:229], s[82:83]
	v_pk_fma_f32 v[228:229], v[170:171], v[228:229], s[84:85]
	v_fmaak_f32 v228, v170, v228, 0x3e2aaaab
	v_fmaak_f32 v229, v171, v229, 0x3e2aaaab
	v_fma_f32 v228, v170, v228, 0.5
	v_fma_f32 v229, v171, v229, 0.5
	v_pk_fma_f32 v[228:229], v[170:171], v[228:229], v[168:169] op_sel_hi:[1,1,0]
	v_pk_mul_f32 v[228:229], v[170:171], v[228:229] neg_lo:[0,1] neg_hi:[0,1]
	v_max_f32_e32 v228, 0, v228
	v_max_f32_e32 v229, 0, v229
	v_sqrt_f32_e32 v228, v228
	v_sqrt_f32_e32 v229, v229
	ds_write_b32 v175, v226 offset:6784
	ds_write_b32 v175, v227 offset:7056
	v_pk_mul_f32 v[228:229], v[126:127], v[228:229]
	s_waitcnt lgkmcnt(2)
	v_pk_mul_f32 v[228:229], v[230:231], v[228:229]
	ds_write2_b32 v233, v228, v229 offset0:32 offset1:100
	ds_read2_b32 v[230:231], v233 offset0:168 offset1:236
	v_add_f32_e64 v124, v130, v189
	v_add_f32_e64 v125, v131, v189
	v_pk_add_f32 v[126:127], v[134:135], v[190:191] op_sel_hi:[1,0]
	v_pk_mul_f32 v[124:125], v[124:125], v[232:233] op_sel_hi:[1,0]
	v_pk_mul_f32 v[126:127], v[126:127], v[232:233] op_sel_hi:[1,0]
	v_exp_f32_e32 v124, v124
	v_exp_f32_e32 v125, v125
	v_exp_f32_e32 v126, v126
	v_exp_f32_e32 v127, v127
	v_pk_add_f32 v[124:125], v[124:125], v[168:169] op_sel_hi:[1,0]
	v_pk_add_f32 v[126:127], v[126:127], v[168:169] op_sel_hi:[1,0]
	v_rcp_f32_e32 v124, v124
	v_rcp_f32_e32 v125, v125
	v_rcp_f32_e32 v126, v126
	v_rcp_f32_e32 v127, v127
	v_pk_mul_f32 v[170:171], v[124:125], v[220:221] op_sel_hi:[1,0]
	v_mul_f32_e32 v226, 0x3fb8aa3b, v170
	v_mul_f32_e32 v227, 0x3fb8aa3b, v171
	v_pk_add_f32 v[170:171], v[170:171], v[170:171]
	v_exp_f32_e32 v226, v226
	v_exp_f32_e32 v227, v227
	v_pk_fma_f32 v[228:229], v[170:171], s[0:1], v[198:199] op_sel_hi:[1,1,0]
	v_pk_fma_f32 v[228:229], v[170:171], v[228:229], s[80:81]
	v_pk_fma_f32 v[228:229], v[170:171], v[228:229], s[82:83]
	v_pk_fma_f32 v[228:229], v[170:171], v[228:229], s[84:85]
	v_fmaak_f32 v228, v170, v228, 0x3e2aaaab
	v_fmaak_f32 v229, v171, v229, 0x3e2aaaab
	v_fma_f32 v228, v170, v228, 0.5
	v_fma_f32 v229, v171, v229, 0.5
	v_pk_fma_f32 v[228:229], v[170:171], v[228:229], v[168:169] op_sel_hi:[1,1,0]
	v_pk_mul_f32 v[228:229], v[170:171], v[228:229] neg_lo:[0,1] neg_hi:[0,1]
	v_max_f32_e32 v228, 0, v228
	v_max_f32_e32 v229, 0, v229
	v_sqrt_f32_e32 v228, v228
	v_sqrt_f32_e32 v229, v229
	ds_write_b32 v175, v226 offset:7328
	ds_write_b32 v175, v227 offset:7600
	v_pk_mul_f32 v[228:229], v[126:127], v[228:229]
	s_waitcnt lgkmcnt(2)
	v_pk_mul_f32 v[228:229], v[230:231], v[228:229]
	ds_write2_b32 v233, v228, v229 offset0:168 offset1:236
	ds_read2_b32 v[230:231], v233 offset0:48 offset1:116
	v_pk_add_f32 v[124:125], v[136:137], v[192:193] op_sel_hi:[1,0]
	v_add_f32_e64 v126, v140, v191
	v_add_f32_e64 v127, v141, v191
	v_pk_mul_f32 v[124:125], v[124:125], v[232:233] op_sel_hi:[1,0]
	v_pk_mul_f32 v[126:127], v[126:127], v[232:233] op_sel_hi:[1,0]
	v_exp_f32_e32 v124, v124
	v_exp_f32_e32 v125, v125
	v_exp_f32_e32 v126, v126
	v_exp_f32_e32 v127, v127
	v_pk_add_f32 v[124:125], v[124:125], v[168:169] op_sel_hi:[1,0]
	v_pk_add_f32 v[126:127], v[126:127], v[168:169] op_sel_hi:[1,0]
	v_rcp_f32_e32 v124, v124
	v_rcp_f32_e32 v125, v125
	v_rcp_f32_e32 v126, v126
	v_rcp_f32_e32 v127, v127
	v_mul_f32_e64 v170, v124, v221
	v_mul_f32_e64 v171, v125, v221
	v_mul_f32_e32 v226, 0x3fb8aa3b, v170
	v_mul_f32_e32 v227, 0x3fb8aa3b, v171
	v_pk_add_f32 v[170:171], v[170:171], v[170:171]
	v_exp_f32_e32 v226, v226
	v_exp_f32_e32 v227, v227
	v_pk_fma_f32 v[228:229], v[170:171], s[0:1], v[198:199] op_sel_hi:[1,1,0]
	v_pk_fma_f32 v[228:229], v[170:171], v[228:229], s[80:81]
	v_pk_fma_f32 v[228:229], v[170:171], v[228:229], s[82:83]
	v_pk_fma_f32 v[228:229], v[170:171], v[228:229], s[84:85]
	v_fmaak_f32 v228, v170, v228, 0x3e2aaaab
	v_fmaak_f32 v229, v171, v229, 0x3e2aaaab
	v_fma_f32 v228, v170, v228, 0.5
	v_fma_f32 v229, v171, v229, 0.5
	v_pk_fma_f32 v[228:229], v[170:171], v[228:229], v[168:169] op_sel_hi:[1,1,0]
	v_pk_mul_f32 v[228:229], v[170:171], v[228:229] neg_lo:[0,1] neg_hi:[0,1]
	v_max_f32_e32 v228, 0, v228
	v_max_f32_e32 v229, 0, v229
	v_sqrt_f32_e32 v228, v228
	v_sqrt_f32_e32 v229, v229
	ds_write_b32 v175, v226 offset:6848
	ds_write_b32 v175, v227 offset:7120
	v_pk_mul_f32 v[228:229], v[126:127], v[228:229]
	s_waitcnt lgkmcnt(2)
	v_pk_mul_f32 v[228:229], v[230:231], v[228:229]
	ds_write2_b32 v233, v228, v229 offset0:48 offset1:116
	ds_read2_b32 v[230:231], v233 offset0:184 offset1:252
	v_pk_add_f32 v[124:125], v[138:139], v[192:193] op_sel_hi:[1,0]
	v_add_f32_e64 v126, v142, v191
	v_add_f32_e64 v127, v143, v191
	v_pk_mul_f32 v[124:125], v[124:125], v[232:233] op_sel_hi:[1,0]
	v_pk_mul_f32 v[126:127], v[126:127], v[232:233] op_sel_hi:[1,0]
	v_exp_f32_e32 v124, v124
	v_exp_f32_e32 v125, v125
	v_exp_f32_e32 v126, v126
	v_exp_f32_e32 v127, v127
	v_pk_add_f32 v[124:125], v[124:125], v[168:169] op_sel_hi:[1,0]
	v_pk_add_f32 v[126:127], v[126:127], v[168:169] op_sel_hi:[1,0]
	v_rcp_f32_e32 v124, v124
	v_rcp_f32_e32 v125, v125
	v_rcp_f32_e32 v126, v126
	v_rcp_f32_e32 v127, v127
	v_mul_f32_e64 v170, v124, v221
	v_mul_f32_e64 v171, v125, v221
	v_mul_f32_e32 v226, 0x3fb8aa3b, v170
	v_mul_f32_e32 v227, 0x3fb8aa3b, v171
	v_pk_add_f32 v[170:171], v[170:171], v[170:171]
	v_exp_f32_e32 v226, v226
	v_exp_f32_e32 v227, v227
	v_pk_fma_f32 v[228:229], v[170:171], s[0:1], v[198:199] op_sel_hi:[1,1,0]
	v_pk_fma_f32 v[228:229], v[170:171], v[228:229], s[80:81]
	v_pk_fma_f32 v[228:229], v[170:171], v[228:229], s[82:83]
	v_pk_fma_f32 v[228:229], v[170:171], v[228:229], s[84:85]
	v_fmaak_f32 v228, v170, v228, 0x3e2aaaab
	v_fmaak_f32 v229, v171, v229, 0x3e2aaaab
	v_fma_f32 v228, v170, v228, 0.5
	v_fma_f32 v229, v171, v229, 0.5
	v_pk_fma_f32 v[228:229], v[170:171], v[228:229], v[168:169] op_sel_hi:[1,1,0]
	v_pk_mul_f32 v[228:229], v[170:171], v[228:229] neg_lo:[0,1] neg_hi:[0,1]
	v_max_f32_e32 v228, 0, v228
	v_max_f32_e32 v229, 0, v229
	v_sqrt_f32_e32 v228, v228
	v_sqrt_f32_e32 v229, v229
	ds_write_b32 v175, v226 offset:7392
	ds_write_b32 v175, v227 offset:7664
	v_pk_mul_f32 v[228:229], v[126:127], v[228:229]
	s_waitcnt lgkmcnt(2)
	v_pk_mul_f32 v[228:229], v[230:231], v[228:229]
	ds_write2_b32 v233, v228, v229 offset0:184 offset1:252
	v_add_u32_e32 v126, 0x1c00, v174
	v_add_u32_e32 v165, 6656, v174
	v_add_u32_e32 v168, 2304, v174
	ds_read2_b32 v[120:121], v165 offset0:0 offset1:68
	ds_read2_b32 v[122:123], v168 offset0:0 offset1:68
	ds_read2_b32 v[124:125], v165 offset0:136 offset1:204
	ds_read2_b32 v[126:127], v168 offset0:136 offset1:204
	v_add_u32_e32 v165, 7744, v174
	v_add_u32_e32 v168, 3392, v174
	ds_read2_b32 v[128:129], v165 offset0:0 offset1:68
	ds_read2_b32 v[130:131], v168 offset0:0 offset1:68
	ds_read2_b32 v[132:133], v165 offset0:136 offset1:204
	ds_read2_b32 v[134:135], v168 offset0:136 offset1:204
	v_add_u32_e32 v165, 8832, v174
	v_add_u32_e32 v168, 4480, v174
	ds_read2_b32 v[136:137], v165 offset0:0 offset1:68
	ds_read2_b32 v[138:139], v168 offset0:0 offset1:68
	ds_read2_b32 v[140:141], v165 offset0:136 offset1:204
	ds_read2_b32 v[142:143], v168 offset0:136 offset1:204
	v_add_u32_e32 v165, 9920, v174
	v_add_u32_e32 v168, 5568, v174
	ds_read2_b32 v[170:171], v165 offset0:0 offset1:68
	ds_read2_b32 v[222:223], v168 offset0:0 offset1:68
	ds_read2_b32 v[224:225], v165 offset0:136 offset1:204
	ds_read2_b32 v[226:227], v168 offset0:136 offset1:204
	s_waitcnt lgkmcnt(14)
	v_fma_f32 v164, v164, v120, v122
	v_mul_f32_e32 v169, v169, v120
	v_fma_f32 v164, v164, v121, v123
	v_mul_f32_e32 v169, v169, v121
	s_waitcnt lgkmcnt(12)
	v_fma_f32 v164, v164, v124, v126
	v_mul_f32_e32 v169, v169, v124
	v_fma_f32 v164, v164, v125, v127
	v_mul_f32_e32 v169, v169, v125
	s_waitcnt lgkmcnt(10)
	v_fma_f32 v164, v164, v128, v130
	v_mul_f32_e32 v169, v169, v128
	v_fma_f32 v164, v164, v129, v131
	v_mul_f32_e32 v169, v169, v129
	s_waitcnt lgkmcnt(8)
	v_fma_f32 v164, v164, v132, v134
	v_mul_f32_e32 v169, v169, v132
	v_fma_f32 v164, v164, v133, v135
	v_mul_f32_e32 v169, v169, v133
	s_waitcnt lgkmcnt(6)
	v_fma_f32 v164, v164, v136, v138
	v_mul_f32_e32 v169, v169, v136
	v_fma_f32 v164, v164, v137, v139
	v_mul_f32_e32 v169, v169, v137
	s_waitcnt lgkmcnt(4)
	v_fma_f32 v164, v164, v140, v142
	v_mul_f32_e32 v169, v169, v140
	v_fma_f32 v164, v164, v141, v143
	v_mul_f32_e32 v169, v169, v141
	s_waitcnt lgkmcnt(2)
	v_fma_f32 v164, v164, v170, v222
	v_mul_f32_e32 v169, v169, v170
	v_fma_f32 v164, v164, v171, v223
	v_mul_f32_e32 v169, v169, v171
	s_waitcnt lgkmcnt(0)
	v_fma_f32 v164, v164, v224, v226
	v_mul_f32_e32 v169, v169, v224
	v_fma_f32 v164, v164, v225, v227
	v_mul_f32_e32 v169, v169, v225
	s_cbranch_scc0 .LBB0_194

.LBB0_274:
	v_add_co_u32_e32 v120, vcc, 0x1200b000, v120
	v_lshl_add_u64 v[122:123], v[190:191], 0, v[166:167]
	s_nop 0
	v_addc_co_u32_e32 v121, vcc, 0, v121, vcc
	global_load_dwordx4 v[124:127], v[122:123], off
	s_add_i32 s20, s20, -1
	global_load_dwordx4 v[120:123], v[120:121], off
	ds_read_b128 v[146:149], v229 offset:11008
	ds_read_b128 v[240:243], v229 offset:11152
	ds_read_b128 v[244:247], v229 offset:11296
	ds_read_b128 v[248:251], v229 offset:11440
	v_lshl_add_u64 v[180:181], v[180:181], 0, s[62:63]
	v_lshl_add_u64 v[190:191], v[190:191], 0, s[62:63]
	s_cmp_lg_u32 s20, 0
	s_waitcnt lgkmcnt(3)
	v_lshlrev_b32_e32 v132, 16, v146
	v_and_b32_e32 v133, 0xffff0000, v146
	v_lshlrev_b32_e32 v128, 16, v147
	v_and_b32_e32 v129, 0xffff0000, v147
	v_lshlrev_b32_e32 v134, 16, v148
	v_and_b32_e32 v135, 0xffff0000, v148
	v_lshlrev_b32_e32 v130, 16, v149
	v_and_b32_e32 v131, 0xffff0000, v149
	ds_read_b128 v[146:149], v229 offset:12160
	v_pk_fma_f32 v[136:137], v[6:7], v[128:129], v[22:23]
	v_pk_fma_f32 v[138:139], v[2:3], v[130:131], v[18:19]
	v_pk_fma_f32 v[132:133], v[4:5], v[132:133], v[20:21]
	v_pk_fma_f32 v[134:135], v[0:1], v[134:135], v[16:17]
	s_waitcnt lgkmcnt(3)
	v_lshlrev_b32_e32 v140, 16, v240
	v_and_b32_e32 v141, 0xffff0000, v240
	v_lshlrev_b32_e32 v128, 16, v241
	v_and_b32_e32 v129, 0xffff0000, v241
	v_lshlrev_b32_e32 v142, 16, v242
	v_and_b32_e32 v143, 0xffff0000, v242
	v_lshlrev_b32_e32 v130, 16, v243
	v_and_b32_e32 v131, 0xffff0000, v243
	ds_read_b128 v[240:243], v229 offset:12304
	v_pk_fma_f32 v[136:137], v[14:15], v[128:129], v[136:137]
	v_pk_fma_f32 v[138:139], v[10:11], v[130:131], v[138:139]
	v_pk_fma_f32 v[132:133], v[12:13], v[140:141], v[132:133]
	v_pk_fma_f32 v[134:135], v[8:9], v[142:143], v[134:135]
	s_waitcnt lgkmcnt(3)
	v_lshlrev_b32_e32 v140, 16, v244
	v_and_b32_e32 v141, 0xffff0000, v244
	v_lshlrev_b32_e32 v128, 16, v245
	v_and_b32_e32 v129, 0xffff0000, v245
	v_lshlrev_b32_e32 v142, 16, v246
	v_and_b32_e32 v143, 0xffff0000, v246
	v_lshlrev_b32_e32 v130, 16, v247
	v_and_b32_e32 v131, 0xffff0000, v247
	ds_read_b128 v[244:247], v229 offset:12448
	v_pk_fma_f32 v[132:133], v[24:25], v[140:141], v[132:133]
	v_pk_fma_f32 v[136:137], v[26:27], v[128:129], v[136:137]
	v_pk_fma_f32 v[140:141], v[28:29], v[142:143], v[134:135]
	v_pk_fma_f32 v[134:135], v[30:31], v[130:131], v[138:139]
	s_waitcnt lgkmcnt(3)
	v_lshlrev_b32_e32 v138, 16, v248
	v_and_b32_e32 v139, 0xffff0000, v248
	v_lshlrev_b32_e32 v128, 16, v249
	v_and_b32_e32 v129, 0xffff0000, v249
	v_lshlrev_b32_e32 v142, 16, v250
	v_and_b32_e32 v143, 0xffff0000, v250
	v_lshlrev_b32_e32 v144, 16, v251
	v_and_b32_e32 v145, 0xffff0000, v251
	ds_read_b128 v[248:251], v229 offset:12592
	v_pk_fma_f32 v[130:131], v[34:35], v[128:129], v[136:137]
	v_pk_fma_f32 v[128:129], v[32:33], v[138:139], v[132:133]
	v_pk_fma_f32 v[134:135], v[38:39], v[144:145], v[134:135]
	v_pk_fma_f32 v[132:133], v[36:37], v[142:143], v[140:141]
	ds_write_b128 v228, v[128:131] offset:2304
	ds_write_b128 v228, v[132:135] offset:2320
	v_cvt_pk_bf16_f32 v128, v128, v129
	v_cvt_pk_bf16_f32 v129, v130, v131
	v_cvt_pk_bf16_f32 v130, v132, v133
	v_cvt_pk_bf16_f32 v131, v134, v135
	ds_write_b128 v229, v[128:131]
	s_waitcnt lgkmcnt(6)
	v_lshlrev_b32_e32 v132, 16, v146
	v_and_b32_e32 v133, 0xffff0000, v146
	v_lshlrev_b32_e32 v128, 16, v147
	v_and_b32_e32 v129, 0xffff0000, v147
	v_lshlrev_b32_e32 v134, 16, v148
	v_and_b32_e32 v135, 0xffff0000, v148
	v_lshlrev_b32_e32 v130, 16, v149
	v_and_b32_e32 v131, 0xffff0000, v149
	v_pk_fma_f32 v[136:137], v[6:7], v[128:129], v[22:23]
	v_pk_fma_f32 v[138:139], v[2:3], v[130:131], v[18:19]
	v_pk_fma_f32 v[132:133], v[4:5], v[132:133], v[20:21]
	v_pk_fma_f32 v[134:135], v[0:1], v[134:135], v[16:17]
	s_waitcnt lgkmcnt(5)
	v_lshlrev_b32_e32 v140, 16, v240
	v_and_b32_e32 v141, 0xffff0000, v240
	v_lshlrev_b32_e32 v128, 16, v241
	v_and_b32_e32 v129, 0xffff0000, v241
	v_lshlrev_b32_e32 v142, 16, v242
	v_and_b32_e32 v143, 0xffff0000, v242
	v_lshlrev_b32_e32 v130, 16, v243
	v_and_b32_e32 v131, 0xffff0000, v243
	v_pk_fma_f32 v[136:137], v[14:15], v[128:129], v[136:137]
	v_pk_fma_f32 v[138:139], v[10:11], v[130:131], v[138:139]
	v_pk_fma_f32 v[132:133], v[12:13], v[140:141], v[132:133]
	v_pk_fma_f32 v[134:135], v[8:9], v[142:143], v[134:135]
	s_waitcnt lgkmcnt(4)
	v_lshlrev_b32_e32 v140, 16, v244
	v_and_b32_e32 v141, 0xffff0000, v244
	v_lshlrev_b32_e32 v128, 16, v245
	v_and_b32_e32 v129, 0xffff0000, v245
	v_lshlrev_b32_e32 v142, 16, v246
	v_and_b32_e32 v143, 0xffff0000, v246
	v_lshlrev_b32_e32 v130, 16, v247
	v_and_b32_e32 v131, 0xffff0000, v247
	v_pk_fma_f32 v[132:133], v[24:25], v[140:141], v[132:133]
	v_pk_fma_f32 v[136:137], v[26:27], v[128:129], v[136:137]
	v_pk_fma_f32 v[140:141], v[28:29], v[142:143], v[134:135]
	v_pk_fma_f32 v[134:135], v[30:31], v[130:131], v[138:139]
	s_waitcnt lgkmcnt(3)
	v_lshlrev_b32_e32 v138, 16, v248
	v_and_b32_e32 v139, 0xffff0000, v248
	v_lshlrev_b32_e32 v128, 16, v249
	v_and_b32_e32 v129, 0xffff0000, v249
	v_lshlrev_b32_e32 v142, 16, v250
	v_and_b32_e32 v143, 0xffff0000, v250
	v_lshlrev_b32_e32 v144, 16, v251
	v_and_b32_e32 v145, 0xffff0000, v251
	v_pk_fma_f32 v[130:131], v[34:35], v[128:129], v[136:137]
	v_pk_fma_f32 v[128:129], v[32:33], v[138:139], v[132:133]
	v_pk_fma_f32 v[134:135], v[38:39], v[144:145], v[134:135]
	v_pk_fma_f32 v[132:133], v[36:37], v[142:143], v[140:141]
	ds_write_b128 v228, v[128:131] offset:4480
	ds_write_b128 v228, v[132:135] offset:4496
	v_cvt_pk_bf16_f32 v128, v128, v129
	v_cvt_pk_bf16_f32 v129, v130, v131
	v_cvt_pk_bf16_f32 v130, v132, v133
	v_cvt_pk_bf16_f32 v131, v134, v135
	ds_write_b128 v229, v[128:131] offset:1152
	s_mov_b32 s0, 0x37d00d01
	s_mov_b32 s1, 0x37d00d01
	s_mov_b32 s26, 0x3ab60b61
	s_mov_b32 s27, 0x3ab60b61
	s_mov_b32 s72, 0x3c088889
	s_mov_b32 s73, 0x3c088889
	ds_read_b128 v[128:131], v222
	ds_read_b128 v[240:243], v222 offset:64
	v_mov_b32_e32 v248, 1.0
	v_mov_b32_e32 v250, 0xbfb8aa3b
	v_add_u32_e32 v249, 2304, v223
	s_waitcnt lgkmcnt(0)
	v_mfma_f32_16x16x32_bf16 v[144:147], v[128:131], v[40:43], 0
	v_mfma_f32_16x16x32_bf16 v[148:151], v[128:131], v[72:75], 0
	v_mfma_f32_16x16x32_bf16 v[144:147], v[240:243], v[44:47], v[144:147]
	v_mfma_f32_16x16x32_bf16 v[148:151], v[240:243], v[76:79], v[148:151]
	s_nop 7
	s_nop 7
	s_nop 7
	ds_read2_b32 v[246:247], v249 offset0:0 offset1:68
	v_add_f32_e64 v132, v144, v173
	v_add_f32_e64 v133, v145, v173
	v_add_f32_e64 v140, v148, v175
	v_add_f32_e64 v141, v149, v175
	v_pk_mul_f32 v[132:133], v[132:133], v[250:251] op_sel_hi:[1,0]
	v_pk_mul_f32 v[140:141], v[140:141], v[250:251] op_sel_hi:[1,0]
	v_exp_f32_e32 v132, v132
	v_exp_f32_e32 v133, v133
	v_exp_f32_e32 v140, v140
	v_exp_f32_e32 v141, v141
	v_pk_add_f32 v[132:133], v[132:133], v[248:249] op_sel_hi:[1,0]
	v_pk_add_f32 v[140:141], v[140:141], v[248:249] op_sel_hi:[1,0]
	v_rcp_f32_e32 v132, v132
	v_rcp_f32_e32 v133, v133
	v_rcp_f32_e32 v140, v140
	v_rcp_f32_e32 v141, v141
	v_pk_mul_f32 v[142:143], v[132:133], v[236:237] op_sel_hi:[1,0]
	v_mul_f32_e32 v192, 0x3fb8aa3b, v142
	v_mul_f32_e32 v193, 0x3fb8aa3b, v143
	v_pk_add_f32 v[142:143], v[142:143], v[142:143]
	v_exp_f32_e32 v192, v192
	v_exp_f32_e32 v193, v193
	v_pk_fma_f32 v[244:245], v[142:143], s[0:1], v[198:199] op_sel_hi:[1,1,0]
	v_pk_fma_f32 v[244:245], v[142:143], v[244:245], s[26:27]
	v_pk_fma_f32 v[244:245], v[142:143], v[244:245], s[72:73]
	v_fmaak_f32 v244, v142, v244, 0x3d2aaaab
	v_fmaak_f32 v245, v143, v245, 0x3d2aaaab
	v_fmaak_f32 v244, v142, v244, 0x3e2aaaab
	v_fmaak_f32 v245, v143, v245, 0x3e2aaaab
	v_fma_f32 v244, v142, v244, 0.5
	v_fma_f32 v245, v143, v245, 0.5
	v_pk_fma_f32 v[244:245], v[142:143], v[244:245], v[248:249] op_sel_hi:[1,1,0]
	v_pk_mul_f32 v[244:245], v[142:143], v[244:245] neg_lo:[0,1] neg_hi:[0,1]
	v_max_f32_e32 v244, 0, v244
	v_max_f32_e32 v245, 0, v245
	v_sqrt_f32_e32 v244, v244
	v_sqrt_f32_e32 v245, v245
	ds_write_b32 v223, v192 offset:6656
	ds_write_b32 v223, v193 offset:6928
	v_pk_mul_f32 v[244:245], v[140:141], v[244:245]
	s_waitcnt lgkmcnt(2)
	v_pk_mul_f32 v[244:245], v[246:247], v[244:245]
	ds_write2_b32 v249, v244, v245 offset0:0 offset1:68
	ds_read2_b32 v[246:247], v249 offset0:136 offset1:204
	v_add_f32_e64 v132, v146, v173
	v_add_f32_e64 v133, v147, v173
	v_add_f32_e64 v140, v150, v175
	v_add_f32_e64 v141, v151, v175
	v_mfma_f32_16x16x32_bf16 v[144:147], v[128:131], v[48:51], 0
	v_mfma_f32_16x16x32_bf16 v[148:151], v[128:131], v[80:83], 0
	v_mfma_f32_16x16x32_bf16 v[144:147], v[240:243], v[52:55], v[144:147]
	v_mfma_f32_16x16x32_bf16 v[148:151], v[240:243], v[84:87], v[148:151]
	v_pk_mul_f32 v[132:133], v[132:133], v[250:251] op_sel_hi:[1,0]
	v_pk_mul_f32 v[140:141], v[140:141], v[250:251] op_sel_hi:[1,0]
	v_exp_f32_e32 v132, v132
	v_exp_f32_e32 v133, v133
	v_exp_f32_e32 v140, v140
	v_exp_f32_e32 v141, v141
	v_pk_add_f32 v[132:133], v[132:133], v[248:249] op_sel_hi:[1,0]
	v_pk_add_f32 v[140:141], v[140:141], v[248:249] op_sel_hi:[1,0]
	v_rcp_f32_e32 v132, v132
	v_rcp_f32_e32 v133, v133
	v_rcp_f32_e32 v140, v140
	v_rcp_f32_e32 v141, v141
	v_pk_mul_f32 v[142:143], v[132:133], v[236:237] op_sel_hi:[1,0]
	v_mul_f32_e32 v192, 0x3fb8aa3b, v142
	v_mul_f32_e32 v193, 0x3fb8aa3b, v143
	v_pk_add_f32 v[142:143], v[142:143], v[142:143]
	v_exp_f32_e32 v192, v192
	v_exp_f32_e32 v193, v193
	v_pk_fma_f32 v[244:245], v[142:143], s[0:1], v[198:199] op_sel_hi:[1,1,0]
	v_pk_fma_f32 v[244:245], v[142:143], v[244:245], s[26:27]
	v_pk_fma_f32 v[244:245], v[142:143], v[244:245], s[72:73]
	v_fmaak_f32 v244, v142, v244, 0x3d2aaaab
	v_fmaak_f32 v245, v143, v245, 0x3d2aaaab
	v_fmaak_f32 v244, v142, v244, 0x3e2aaaab
	v_fmaak_f32 v245, v143, v245, 0x3e2aaaab
	v_fma_f32 v244, v142, v244, 0.5
	v_fma_f32 v245, v143, v245, 0.5
	v_pk_fma_f32 v[244:245], v[142:143], v[244:245], v[248:249] op_sel_hi:[1,1,0]
	v_pk_mul_f32 v[244:245], v[142:143], v[244:245] neg_lo:[0,1] neg_hi:[0,1]
	v_max_f32_e32 v244, 0, v244
	v_max_f32_e32 v245, 0, v245
	v_sqrt_f32_e32 v244, v244
	v_sqrt_f32_e32 v245, v245
	ds_write_b32 v223, v192 offset:7200
	ds_write_b32 v223, v193 offset:7472
	v_pk_mul_f32 v[244:245], v[140:141], v[244:245]
	s_waitcnt lgkmcnt(2)
	v_pk_mul_f32 v[244:245], v[246:247], v[244:245]
	ds_write2_b32 v249, v244, v245 offset0:136 offset1:204
	ds_read2_b32 v[246:247], v249 offset0:16 offset1:84
	v_pk_add_f32 v[132:133], v[144:145], v[230:231] op_sel_hi:[1,0]
	v_add_f32_e64 v140, v148, v231
	v_add_f32_e64 v141, v149, v231
	v_pk_mul_f32 v[132:133], v[132:133], v[250:251] op_sel_hi:[1,0]
	v_pk_mul_f32 v[140:141], v[140:141], v[250:251] op_sel_hi:[1,0]
	v_exp_f32_e32 v132, v132
	v_exp_f32_e32 v133, v133
	v_exp_f32_e32 v140, v140
	v_exp_f32_e32 v141, v141
	v_pk_add_f32 v[132:133], v[132:133], v[248:249] op_sel_hi:[1,0]
	v_pk_add_f32 v[140:141], v[140:141], v[248:249] op_sel_hi:[1,0]
	v_rcp_f32_e32 v132, v132
	v_rcp_f32_e32 v133, v133
	v_rcp_f32_e32 v140, v140
	v_rcp_f32_e32 v141, v141
	v_mul_f32_e64 v142, v132, v237
	v_mul_f32_e64 v143, v133, v237
	v_mul_f32_e32 v192, 0x3fb8aa3b, v142
	v_mul_f32_e32 v193, 0x3fb8aa3b, v143
	v_pk_add_f32 v[142:143], v[142:143], v[142:143]
	v_exp_f32_e32 v192, v192
	v_exp_f32_e32 v193, v193
	v_pk_fma_f32 v[244:245], v[142:143], s[0:1], v[198:199] op_sel_hi:[1,1,0]
	v_pk_fma_f32 v[244:245], v[142:143], v[244:245], s[26:27]
	v_pk_fma_f32 v[244:245], v[142:143], v[244:245], s[72:73]
	v_fmaak_f32 v244, v142, v244, 0x3d2aaaab
	v_fmaak_f32 v245, v143, v245, 0x3d2aaaab
	v_fmaak_f32 v244, v142, v244, 0x3e2aaaab
	v_fmaak_f32 v245, v143, v245, 0x3e2aaaab
	v_fma_f32 v244, v142, v244, 0.5
	v_fma_f32 v245, v143, v245, 0.5
	v_pk_fma_f32 v[244:245], v[142:143], v[244:245], v[248:249] op_sel_hi:[1,1,0]
	v_pk_mul_f32 v[244:245], v[142:143], v[244:245] neg_lo:[0,1] neg_hi:[0,1]
	v_max_f32_e32 v244, 0, v244
	v_max_f32_e32 v245, 0, v245
	v_sqrt_f32_e32 v244, v244
	v_sqrt_f32_e32 v245, v245
	ds_write_b32 v223, v192 offset:6720
	ds_write_b32 v223, v193 offset:6992
	v_pk_mul_f32 v[244:245], v[140:141], v[244:245]
	s_waitcnt lgkmcnt(2)
	v_pk_mul_f32 v[244:245], v[246:247], v[244:245]
	ds_write2_b32 v249, v244, v245 offset0:16 offset1:84
	ds_read2_b32 v[246:247], v249 offset0:152 offset1:220
	v_pk_add_f32 v[132:133], v[146:147], v[230:231] op_sel_hi:[1,0]
	v_add_f32_e64 v140, v150, v231
	v_add_f32_e64 v141, v151, v231
	v_mfma_f32_16x16x32_bf16 v[144:147], v[128:131], v[56:59], 0
	v_mfma_f32_16x16x32_bf16 v[148:151], v[128:131], v[88:91], 0
	v_mfma_f32_16x16x32_bf16 v[144:147], v[240:243], v[60:63], v[144:147]
	v_mfma_f32_16x16x32_bf16 v[148:151], v[240:243], v[92:95], v[148:151]
	v_pk_mul_f32 v[132:133], v[132:133], v[250:251] op_sel_hi:[1,0]
	v_pk_mul_f32 v[140:141], v[140:141], v[250:251] op_sel_hi:[1,0]
	v_exp_f32_e32 v132, v132
	v_exp_f32_e32 v133, v133
	v_exp_f32_e32 v140, v140
	v_exp_f32_e32 v141, v141
	v_pk_add_f32 v[132:133], v[132:133], v[248:249] op_sel_hi:[1,0]
	v_pk_add_f32 v[140:141], v[140:141], v[248:249] op_sel_hi:[1,0]
	v_rcp_f32_e32 v132, v132
	v_rcp_f32_e32 v133, v133
	v_rcp_f32_e32 v140, v140
	v_rcp_f32_e32 v141, v141
	v_mul_f32_e64 v142, v132, v237
	v_mul_f32_e64 v143, v133, v237
	v_mul_f32_e32 v192, 0x3fb8aa3b, v142
	v_mul_f32_e32 v193, 0x3fb8aa3b, v143
	v_pk_add_f32 v[142:143], v[142:143], v[142:143]
	v_exp_f32_e32 v192, v192
	v_exp_f32_e32 v193, v193
	v_pk_fma_f32 v[244:245], v[142:143], s[0:1], v[198:199] op_sel_hi:[1,1,0]
	v_pk_fma_f32 v[244:245], v[142:143], v[244:245], s[26:27]
	v_pk_fma_f32 v[244:245], v[142:143], v[244:245], s[72:73]
	v_fmaak_f32 v244, v142, v244, 0x3d2aaaab
	v_fmaak_f32 v245, v143, v245, 0x3d2aaaab
	v_fmaak_f32 v244, v142, v244, 0x3e2aaaab
	v_fmaak_f32 v245, v143, v245, 0x3e2aaaab
	v_fma_f32 v244, v142, v244, 0.5
	v_fma_f32 v245, v143, v245, 0.5
	v_pk_fma_f32 v[244:245], v[142:143], v[244:245], v[248:249] op_sel_hi:[1,1,0]
	v_pk_mul_f32 v[244:245], v[142:143], v[244:245] neg_lo:[0,1] neg_hi:[0,1]
	v_max_f32_e32 v244, 0, v244
	v_max_f32_e32 v245, 0, v245
	v_sqrt_f32_e32 v244, v244
	v_sqrt_f32_e32 v245, v245
	ds_write_b32 v223, v192 offset:7264
	ds_write_b32 v223, v193 offset:7536
	v_pk_mul_f32 v[244:245], v[140:141], v[244:245]
	s_waitcnt lgkmcnt(2)
	v_pk_mul_f32 v[244:245], v[246:247], v[244:245]
	ds_write2_b32 v249, v244, v245 offset0:152 offset1:220
	ds_read2_b32 v[246:247], v249 offset0:32 offset1:100
	v_pk_add_f32 v[132:133], v[144:145], v[232:233] op_sel_hi:[1,0]
	v_add_f32_e64 v140, v148, v233
	v_add_f32_e64 v141, v149, v233
	v_pk_mul_f32 v[132:133], v[132:133], v[250:251] op_sel_hi:[1,0]
	v_pk_mul_f32 v[140:141], v[140:141], v[250:251] op_sel_hi:[1,0]
	v_exp_f32_e32 v132, v132
	v_exp_f32_e32 v133, v133
	v_exp_f32_e32 v140, v140
	v_exp_f32_e32 v141, v141
	v_pk_add_f32 v[132:133], v[132:133], v[248:249] op_sel_hi:[1,0]
	v_pk_add_f32 v[140:141], v[140:141], v[248:249] op_sel_hi:[1,0]
	v_rcp_f32_e32 v132, v132
	v_rcp_f32_e32 v133, v133
	v_rcp_f32_e32 v140, v140
	v_rcp_f32_e32 v141, v141
	v_pk_mul_f32 v[142:143], v[132:133], v[238:239] op_sel_hi:[1,0]
	v_mul_f32_e32 v192, 0x3fb8aa3b, v142
	v_mul_f32_e32 v193, 0x3fb8aa3b, v143
	v_pk_add_f32 v[142:143], v[142:143], v[142:143]
	v_exp_f32_e32 v192, v192
	v_exp_f32_e32 v193, v193
	v_pk_fma_f32 v[244:245], v[142:143], s[0:1], v[198:199] op_sel_hi:[1,1,0]
	v_pk_fma_f32 v[244:245], v[142:143], v[244:245], s[26:27]
	v_pk_fma_f32 v[244:245], v[142:143], v[244:245], s[72:73]
	v_fmaak_f32 v244, v142, v244, 0x3d2aaaab
	v_fmaak_f32 v245, v143, v245, 0x3d2aaaab
	v_fmaak_f32 v244, v142, v244, 0x3e2aaaab
	v_fmaak_f32 v245, v143, v245, 0x3e2aaaab
	v_fma_f32 v244, v142, v244, 0.5
	v_fma_f32 v245, v143, v245, 0.5
	v_pk_fma_f32 v[244:245], v[142:143], v[244:245], v[248:249] op_sel_hi:[1,1,0]
	v_pk_mul_f32 v[244:245], v[142:143], v[244:245] neg_lo:[0,1] neg_hi:[0,1]
	v_max_f32_e32 v244, 0, v244
	v_max_f32_e32 v245, 0, v245
	v_sqrt_f32_e32 v244, v244
	v_sqrt_f32_e32 v245, v245
	ds_write_b32 v223, v192 offset:6784
	ds_write_b32 v223, v193 offset:7056
	v_pk_mul_f32 v[244:245], v[140:141], v[244:245]
	s_waitcnt lgkmcnt(2)
	v_pk_mul_f32 v[244:245], v[246:247], v[244:245]
	ds_write2_b32 v249, v244, v245 offset0:32 offset1:100
	ds_read2_b32 v[246:247], v249 offset0:168 offset1:236
	v_pk_add_f32 v[132:133], v[146:147], v[232:233] op_sel_hi:[1,0]
	v_add_f32_e64 v140, v150, v233
	v_add_f32_e64 v141, v151, v233
	v_mfma_f32_16x16x32_bf16 v[144:147], v[128:131], v[64:67], 0
	v_mfma_f32_16x16x32_bf16 v[148:151], v[128:131], v[100:103], 0
	v_mfma_f32_16x16x32_bf16 v[144:147], v[240:243], v[68:71], v[144:147]
	v_mfma_f32_16x16x32_bf16 v[148:151], v[240:243], v[104:107], v[148:151]
	v_pk_mul_f32 v[132:133], v[132:133], v[250:251] op_sel_hi:[1,0]
	v_pk_mul_f32 v[140:141], v[140:141], v[250:251] op_sel_hi:[1,0]
	v_exp_f32_e32 v132, v132
	v_exp_f32_e32 v133, v133
	v_exp_f32_e32 v140, v140
	v_exp_f32_e32 v141, v141
	v_pk_add_f32 v[132:133], v[132:133], v[248:249] op_sel_hi:[1,0]
	v_pk_add_f32 v[140:141], v[140:141], v[248:249] op_sel_hi:[1,0]
	v_rcp_f32_e32 v132, v132
	v_rcp_f32_e32 v133, v133
	v_rcp_f32_e32 v140, v140
	v_rcp_f32_e32 v141, v141
	v_pk_mul_f32 v[142:143], v[132:133], v[238:239] op_sel_hi:[1,0]
	v_mul_f32_e32 v192, 0x3fb8aa3b, v142
	v_mul_f32_e32 v193, 0x3fb8aa3b, v143
	v_pk_add_f32 v[142:143], v[142:143], v[142:143]
	v_exp_f32_e32 v192, v192
	v_exp_f32_e32 v193, v193
	v_pk_fma_f32 v[244:245], v[142:143], s[0:1], v[198:199] op_sel_hi:[1,1,0]
	v_pk_fma_f32 v[244:245], v[142:143], v[244:245], s[26:27]
	v_pk_fma_f32 v[244:245], v[142:143], v[244:245], s[72:73]
	v_fmaak_f32 v244, v142, v244, 0x3d2aaaab
	v_fmaak_f32 v245, v143, v245, 0x3d2aaaab
	v_fmaak_f32 v244, v142, v244, 0x3e2aaaab
	v_fmaak_f32 v245, v143, v245, 0x3e2aaaab
	v_fma_f32 v244, v142, v244, 0.5
	v_fma_f32 v245, v143, v245, 0.5
	v_pk_fma_f32 v[244:245], v[142:143], v[244:245], v[248:249] op_sel_hi:[1,1,0]
	v_pk_mul_f32 v[244:245], v[142:143], v[244:245] neg_lo:[0,1] neg_hi:[0,1]
	v_max_f32_e32 v244, 0, v244
	v_max_f32_e32 v245, 0, v245
	v_sqrt_f32_e32 v244, v244
	v_sqrt_f32_e32 v245, v245
	ds_write_b32 v223, v192 offset:7328
	ds_write_b32 v223, v193 offset:7600
	v_pk_mul_f32 v[244:245], v[140:141], v[244:245]
	s_waitcnt lgkmcnt(2)
	v_pk_mul_f32 v[244:245], v[246:247], v[244:245]
	ds_write2_b32 v249, v244, v245 offset0:168 offset1:236
	ds_read2_b32 v[246:247], v249 offset0:48 offset1:116
	v_add_f32_e64 v132, v144, v235
	v_add_f32_e64 v133, v145, v235
	v_pk_add_f32 v[140:141], v[148:149], v[234:235] op_sel_hi:[1,0]
	v_pk_mul_f32 v[132:133], v[132:133], v[250:251] op_sel_hi:[1,0]
	v_pk_mul_f32 v[140:141], v[140:141], v[250:251] op_sel_hi:[1,0]
	v_exp_f32_e32 v132, v132
	v_exp_f32_e32 v133, v133
	v_exp_f32_e32 v140, v140
	v_exp_f32_e32 v141, v141
	v_pk_add_f32 v[132:133], v[132:133], v[248:249] op_sel_hi:[1,0]
	v_pk_add_f32 v[140:141], v[140:141], v[248:249] op_sel_hi:[1,0]
	v_rcp_f32_e32 v132, v132
	v_rcp_f32_e32 v133, v133
	v_rcp_f32_e32 v140, v140
	v_rcp_f32_e32 v141, v141
	v_mul_f32_e64 v142, v132, v239
	v_mul_f32_e64 v143, v133, v239
	v_mul_f32_e32 v192, 0x3fb8aa3b, v142
	v_mul_f32_e32 v193, 0x3fb8aa3b, v143
	v_pk_add_f32 v[142:143], v[142:143], v[142:143]
	v_exp_f32_e32 v192, v192
	v_exp_f32_e32 v193, v193
	v_pk_fma_f32 v[244:245], v[142:143], s[0:1], v[198:199] op_sel_hi:[1,1,0]
	v_pk_fma_f32 v[244:245], v[142:143], v[244:245], s[26:27]
	v_pk_fma_f32 v[244:245], v[142:143], v[244:245], s[72:73]
	v_fmaak_f32 v244, v142, v244, 0x3d2aaaab
	v_fmaak_f32 v245, v143, v245, 0x3d2aaaab
	v_fmaak_f32 v244, v142, v244, 0x3e2aaaab
	v_fmaak_f32 v245, v143, v245, 0x3e2aaaab
	v_fma_f32 v244, v142, v244, 0.5
	v_fma_f32 v245, v143, v245, 0.5
	v_pk_fma_f32 v[244:245], v[142:143], v[244:245], v[248:249] op_sel_hi:[1,1,0]
	v_pk_mul_f32 v[244:245], v[142:143], v[244:245] neg_lo:[0,1] neg_hi:[0,1]
	v_max_f32_e32 v244, 0, v244
	v_max_f32_e32 v245, 0, v245
	v_sqrt_f32_e32 v244, v244
	v_sqrt_f32_e32 v245, v245
	ds_write_b32 v223, v192 offset:6848
	ds_write_b32 v223, v193 offset:7120
	v_pk_mul_f32 v[244:245], v[140:141], v[244:245]
	s_waitcnt lgkmcnt(2)
	v_pk_mul_f32 v[244:245], v[246:247], v[244:245]
	ds_write2_b32 v249, v244, v245 offset0:48 offset1:116
	ds_read2_b32 v[246:247], v249 offset0:184 offset1:252
	v_add_f32_e64 v132, v146, v235
	v_add_f32_e64 v133, v147, v235
	v_pk_add_f32 v[140:141], v[150:151], v[234:235] op_sel_hi:[1,0]
	v_pk_mul_f32 v[132:133], v[132:133], v[250:251] op_sel_hi:[1,0]
	v_pk_mul_f32 v[140:141], v[140:141], v[250:251] op_sel_hi:[1,0]
	v_exp_f32_e32 v132, v132
	v_exp_f32_e32 v133, v133
	v_exp_f32_e32 v140, v140
	v_exp_f32_e32 v141, v141
	v_pk_add_f32 v[132:133], v[132:133], v[248:249] op_sel_hi:[1,0]
	v_pk_add_f32 v[140:141], v[140:141], v[248:249] op_sel_hi:[1,0]
	v_rcp_f32_e32 v132, v132
	v_rcp_f32_e32 v133, v133
	v_rcp_f32_e32 v140, v140
	v_rcp_f32_e32 v141, v141
	v_mul_f32_e64 v142, v132, v239
	v_mul_f32_e64 v143, v133, v239
	v_mul_f32_e32 v192, 0x3fb8aa3b, v142
	v_mul_f32_e32 v193, 0x3fb8aa3b, v143
	v_pk_add_f32 v[142:143], v[142:143], v[142:143]
	v_exp_f32_e32 v192, v192
	v_exp_f32_e32 v193, v193
	v_pk_fma_f32 v[244:245], v[142:143], s[0:1], v[198:199] op_sel_hi:[1,1,0]
	v_pk_fma_f32 v[244:245], v[142:143], v[244:245], s[26:27]
	v_pk_fma_f32 v[244:245], v[142:143], v[244:245], s[72:73]
	v_fmaak_f32 v244, v142, v244, 0x3d2aaaab
	v_fmaak_f32 v245, v143, v245, 0x3d2aaaab
	v_fmaak_f32 v244, v142, v244, 0x3e2aaaab
	v_fmaak_f32 v245, v143, v245, 0x3e2aaaab
	v_fma_f32 v244, v142, v244, 0.5
	v_fma_f32 v245, v143, v245, 0.5
	v_pk_fma_f32 v[244:245], v[142:143], v[244:245], v[248:249] op_sel_hi:[1,1,0]
	v_pk_mul_f32 v[244:245], v[142:143], v[244:245] neg_lo:[0,1] neg_hi:[0,1]
	v_max_f32_e32 v244, 0, v244
	v_max_f32_e32 v245, 0, v245
	v_sqrt_f32_e32 v244, v244
	v_sqrt_f32_e32 v245, v245
	ds_write_b32 v223, v192 offset:7392
	ds_write_b32 v223, v193 offset:7664
	v_pk_mul_f32 v[244:245], v[140:141], v[244:245]
	s_waitcnt lgkmcnt(2)
	v_pk_mul_f32 v[244:245], v[246:247], v[244:245]
	ds_write2_b32 v249, v244, v245 offset0:184 offset1:252
	s_waitcnt vmcnt(1)
	v_lshlrev_b32_e32 v139, 16, v127
	v_and_b32_e32 v127, 0xffff0000, v127
	v_lshlrev_b32_e32 v137, 16, v125
	v_and_b32_e32 v125, 0xffff0000, v125
	v_lshlrev_b32_e32 v138, 16, v126
	v_and_b32_e32 v126, 0xffff0000, v126
	v_add_u32_e32 v134, 0xa00, v227
	v_add_u32_e32 v141, 6656, v227
	v_add_u32_e32 v176, 2304, v227
	ds_read2_b32 v[128:129], v141 offset0:0 offset1:68
	ds_read2_b32 v[130:131], v176 offset0:0 offset1:68
	ds_read2_b32 v[132:133], v141 offset0:136 offset1:204
	ds_read2_b32 v[134:135], v176 offset0:136 offset1:204
	v_add_u32_e32 v141, 7744, v227
	v_add_u32_e32 v176, 3392, v227
	ds_read2_b32 v[142:143], v141 offset0:0 offset1:68
	ds_read2_b32 v[144:145], v176 offset0:0 offset1:68
	ds_read2_b32 v[146:147], v141 offset0:136 offset1:204
	ds_read2_b32 v[148:149], v176 offset0:136 offset1:204
	v_add_u32_e32 v141, 8832, v227
	v_add_u32_e32 v176, 4480, v227
	ds_read2_b32 v[150:151], v141 offset0:0 offset1:68
	ds_read2_b32 v[192:193], v176 offset0:0 offset1:68
	ds_read2_b32 v[240:241], v141 offset0:136 offset1:204
	ds_read2_b32 v[242:243], v176 offset0:136 offset1:204
	v_add_u32_e32 v141, 9920, v227
	v_add_u32_e32 v176, 5568, v227
	ds_read2_b32 v[244:245], v141 offset0:0 offset1:68
	ds_read2_b32 v[246:247], v176 offset0:0 offset1:68
	ds_read2_b32 v[248:249], v141 offset0:136 offset1:204
	ds_read2_b32 v[250:251], v176 offset0:136 offset1:204
	s_waitcnt lgkmcnt(14)
	v_fma_f32 v130, v177, v128, v130
	v_fma_f32 v131, v130, v129, v131
	s_waitcnt lgkmcnt(12)
	v_fma_f32 v134, v131, v132, v134
	v_fma_f32 v135, v134, v133, v135
	s_waitcnt lgkmcnt(10)
	v_fma_f32 v144, v135, v142, v144
	v_fma_f32 v145, v144, v143, v145
	s_waitcnt lgkmcnt(8)
	v_fma_f32 v148, v145, v146, v148
	v_fma_f32 v149, v148, v147, v149
	s_waitcnt lgkmcnt(6)
	v_fma_f32 v192, v149, v150, v192
	v_fma_f32 v193, v192, v151, v193
	s_waitcnt lgkmcnt(4)
	v_fma_f32 v242, v193, v240, v242
	v_fma_f32 v243, v242, v241, v243
	s_waitcnt lgkmcnt(2)
	v_fma_f32 v246, v243, v244, v246
	v_fma_f32 v247, v246, v245, v247
	s_waitcnt lgkmcnt(0)
	v_fma_f32 v250, v247, v248, v250
	v_fma_f32 v251, v250, v249, v251
	v_add_u32_e32 v176, 2304, v227
	ds_write2_b32 v176, v130, v131 offset0:0 offset1:68
	ds_write2_b32 v176, v134, v135 offset0:136 offset1:204
	v_add_u32_e32 v176, 3392, v227
	ds_write2_b32 v176, v144, v145 offset0:0 offset1:68
	ds_write2_b32 v176, v148, v149 offset0:136 offset1:204
	v_add_u32_e32 v176, 4480, v227
	ds_write2_b32 v176, v192, v193 offset0:0 offset1:68
	ds_write2_b32 v176, v242, v243 offset0:136 offset1:204
	v_add_u32_e32 v176, 5568, v227
	ds_write2_b32 v176, v246, v247 offset0:0 offset1:68
	ds_write2_b32 v176, v250, v251 offset0:136 offset1:204
	v_mov_b32_e32 v177, v251
	v_lshlrev_b32_e32 v136, 16, v124
	v_mul_f32_e32 v140, 0x3d372713, v136
	v_mul_f32_e32 v140, v140, v136
	v_and_b32_e32 v124, 0xffff0000, v124
	ds_read_b128 v[128:131], v228 offset:2304
	ds_read_b128 v[132:135], v228 offset:2320
	s_waitcnt lgkmcnt(1)
	v_mul_f32_e32 v128, v128, v136
	v_fmac_f32_e32 v136, v140, v136
	v_mul_f32_e32 v136, 0x3fcc422a, v136
	v_mul_f32_e32 v136, 0xbfb8aa3b, v136
	v_exp_f32_e32 v136, v136
	v_mul_f32_e32 v129, v129, v124
	v_add_f32_e32 v136, 1.0, v136
	v_rcp_f32_e32 v136, v136
	s_nop 0
	v_mul_f32_e32 v128, v136, v128
	v_mul_f32_e32 v136, 0x3d372713, v124
	v_mul_f32_e32 v136, v136, v124
	v_fmac_f32_e32 v124, v136, v124
	v_mul_f32_e32 v124, 0x3fcc422a, v124
	v_mul_f32_e32 v124, 0xbfb8aa3b, v124
	v_exp_f32_e32 v124, v124
	s_nop 0
	v_add_f32_e32 v124, 1.0, v124
	v_rcp_f32_e32 v124, v124
	s_nop 0
	v_mul_f32_e32 v124, v124, v129
	v_mul_f32_e32 v129, v130, v137
	v_mul_f32_e32 v130, 0x3d372713, v137
	v_mul_f32_e32 v130, v130, v137
	v_fmac_f32_e32 v137, v130, v137
	v_mul_f32_e32 v130, 0x3fcc422a, v137
	v_mul_f32_e32 v130, 0xbfb8aa3b, v130
	v_exp_f32_e32 v130, v130
	v_cvt_pk_bf16_f32 v124, v128, v124
	s_nop 0
	v_add_f32_e32 v130, 1.0, v130
	v_rcp_f32_e32 v130, v130
	s_nop 0
	v_mul_f32_e32 v129, v130, v129
	v_mul_f32_e32 v130, v131, v125
	v_mul_f32_e32 v131, 0x3d372713, v125
	v_mul_f32_e32 v131, v131, v125
	v_fmac_f32_e32 v125, v131, v125
	v_mul_f32_e32 v125, 0x3fcc422a, v125
	v_mul_f32_e32 v125, 0xbfb8aa3b, v125
	v_exp_f32_e32 v125, v125
	v_mul_f32_e32 v131, 0x3d372713, v138
	v_mul_f32_e32 v131, v131, v138
	v_add_f32_e32 v125, 1.0, v125
	v_rcp_f32_e32 v125, v125
	s_nop 0
	v_mul_f32_e32 v125, v125, v130
	s_waitcnt lgkmcnt(0)
	v_mul_f32_e32 v130, v132, v138
	v_fmac_f32_e32 v138, v131, v138
	v_mul_f32_e32 v131, 0x3fcc422a, v138
	v_mul_f32_e32 v131, 0xbfb8aa3b, v131
	v_exp_f32_e32 v131, v131
	v_mul_f32_e32 v132, 0x3d372713, v126
	v_mul_f32_e32 v132, v132, v126
	v_cvt_pk_bf16_f32 v125, v129, v125
	v_add_f32_e32 v131, 1.0, v131
	v_rcp_f32_e32 v131, v131
	v_lshl_add_u64 v[128:129], v[188:189], 0, v[166:167]
	v_lshl_add_u64 v[188:189], v[188:189], 0, s[60:61]
	v_mul_f32_e32 v130, v131, v130
	v_mul_f32_e32 v131, v133, v126
	v_fmac_f32_e32 v126, v132, v126
	v_mul_f32_e32 v126, 0x3fcc422a, v126
	v_mul_f32_e32 v126, 0xbfb8aa3b, v126
	v_exp_f32_e32 v126, v126
	v_mul_f32_e32 v132, 0x3d372713, v139
	v_mul_f32_e32 v132, v132, v139
	v_mul_f32_e32 v133, 0x3d372713, v127
	v_add_f32_e32 v126, 1.0, v126
	v_rcp_f32_e32 v126, v126
	v_mul_f32_e32 v133, v133, v127
	v_mul_f32_e32 v126, v126, v131
	v_mul_f32_e32 v131, v134, v139
	v_fmac_f32_e32 v139, v132, v139
	v_mul_f32_e32 v132, 0x3fcc422a, v139
	v_mul_f32_e32 v132, 0xbfb8aa3b, v132
	v_exp_f32_e32 v132, v132
	v_cvt_pk_bf16_f32 v126, v130, v126
	s_waitcnt vmcnt(0)
	v_lshlrev_b32_e32 v134, 16, v122
	v_and_b32_e32 v122, 0xffff0000, v122
	v_add_f32_e32 v132, 1.0, v132
	v_rcp_f32_e32 v132, v132
	s_nop 0
	v_mul_f32_e32 v131, v132, v131
	v_mul_f32_e32 v132, v135, v127
	v_fmac_f32_e32 v127, v133, v127
	v_mul_f32_e32 v127, 0x3fcc422a, v127
	v_mul_f32_e32 v127, 0xbfb8aa3b, v127
	v_exp_f32_e32 v127, v127
	v_lshlrev_b32_e32 v133, 16, v121
	v_and_b32_e32 v121, 0xffff0000, v121
	v_lshlrev_b32_e32 v135, 16, v123
	v_add_f32_e32 v127, 1.0, v127
	v_rcp_f32_e32 v127, v127
	v_and_b32_e32 v123, 0xffff0000, v123
	v_mul_f32_e32 v127, v127, v132
	v_cvt_pk_bf16_f32 v127, v131, v127
	global_store_dwordx4 v[128:129], v[124:127], off
	ds_read_b128 v[124:127], v228 offset:4480
	ds_read_b128 v[128:131], v228 offset:4496
	v_lshlrev_b32_e32 v132, 16, v120
	v_mul_f32_e32 v136, 0x3d372713, v132
	v_mul_f32_e32 v136, v136, v132
	s_waitcnt lgkmcnt(1)
	v_mul_f32_e32 v124, v124, v132
	v_fmac_f32_e32 v132, v136, v132
	v_mul_f32_e32 v132, 0x3fcc422a, v132
	v_mul_f32_e32 v132, 0xbfb8aa3b, v132
	v_exp_f32_e32 v132, v132
	v_and_b32_e32 v120, 0xffff0000, v120
	v_mul_f32_e32 v125, v125, v120
	v_add_f32_e32 v132, 1.0, v132
	v_rcp_f32_e32 v132, v132
	s_nop 0
	v_mul_f32_e32 v124, v132, v124
	v_mul_f32_e32 v132, 0x3d372713, v120
	v_mul_f32_e32 v132, v132, v120
	v_fmac_f32_e32 v120, v132, v120
	v_mul_f32_e32 v120, 0x3fcc422a, v120
	v_mul_f32_e32 v120, 0xbfb8aa3b, v120
	v_exp_f32_e32 v120, v120
	s_nop 0
	v_add_f32_e32 v120, 1.0, v120
	v_rcp_f32_e32 v120, v120
	s_nop 0
	v_mul_f32_e32 v120, v120, v125
	v_mul_f32_e32 v125, v126, v133
	v_mul_f32_e32 v126, 0x3d372713, v133
	v_mul_f32_e32 v126, v126, v133
	v_fmac_f32_e32 v133, v126, v133
	v_mul_f32_e32 v126, 0x3fcc422a, v133
	v_mul_f32_e32 v126, 0xbfb8aa3b, v126
	v_exp_f32_e32 v126, v126
	v_cvt_pk_bf16_f32 v120, v124, v120
	s_nop 0
	v_add_f32_e32 v126, 1.0, v126
	v_rcp_f32_e32 v126, v126
	s_nop 0
	v_mul_f32_e32 v125, v126, v125
	v_mul_f32_e32 v126, v127, v121
	v_mul_f32_e32 v127, 0x3d372713, v121
	v_mul_f32_e32 v127, v127, v121
	v_fmac_f32_e32 v121, v127, v121
	v_mul_f32_e32 v121, 0x3fcc422a, v121
	v_mul_f32_e32 v121, 0xbfb8aa3b, v121
	v_exp_f32_e32 v121, v121
	v_mul_f32_e32 v127, 0x3d372713, v134
	v_mul_f32_e32 v127, v127, v134
	v_add_f32_e32 v121, 1.0, v121
	v_rcp_f32_e32 v121, v121
	s_nop 0
	v_mul_f32_e32 v121, v121, v126
	s_waitcnt lgkmcnt(0)
	v_mul_f32_e32 v126, v128, v134
	v_fmac_f32_e32 v134, v127, v134
	v_mul_f32_e32 v127, 0x3fcc422a, v134
	v_mul_f32_e32 v127, 0xbfb8aa3b, v127
	v_exp_f32_e32 v127, v127
	v_mul_f32_e32 v128, 0x3d372713, v122
	v_mul_f32_e32 v128, v128, v122
	v_cvt_pk_bf16_f32 v121, v125, v121
	v_add_f32_e32 v127, 1.0, v127
	v_rcp_f32_e32 v127, v127
	v_lshl_add_u64 v[124:125], v[178:179], 0, v[166:167]
	v_lshl_add_u64 v[178:179], v[178:179], 0, s[60:61]
	v_mul_f32_e32 v126, v127, v126
	v_mul_f32_e32 v127, v129, v122
	v_fmac_f32_e32 v122, v128, v122
	v_mul_f32_e32 v122, 0x3fcc422a, v122
	v_mul_f32_e32 v122, 0xbfb8aa3b, v122
	v_exp_f32_e32 v122, v122
	v_mul_f32_e32 v128, 0x3d372713, v135
	v_mul_f32_e32 v128, v128, v135
	v_mul_f32_e32 v129, 0x3d372713, v123
	v_add_f32_e32 v122, 1.0, v122
	v_rcp_f32_e32 v122, v122
	v_mul_f32_e32 v129, v129, v123
	v_mul_f32_e32 v122, v122, v127
	v_mul_f32_e32 v127, v130, v135
	v_fmac_f32_e32 v135, v128, v135
	v_mul_f32_e32 v128, 0x3fcc422a, v135
	v_mul_f32_e32 v128, 0xbfb8aa3b, v128
	v_exp_f32_e32 v128, v128
	v_cvt_pk_bf16_f32 v122, v126, v122
	s_nop 0
	v_add_f32_e32 v128, 1.0, v128
	v_rcp_f32_e32 v128, v128
	s_nop 0
	v_mul_f32_e32 v127, v128, v127
	v_mul_f32_e32 v128, v131, v123
	v_fmac_f32_e32 v123, v129, v123
	v_mul_f32_e32 v123, 0x3fcc422a, v123
	v_mul_f32_e32 v123, 0xbfb8aa3b, v123
	v_exp_f32_e32 v123, v123
	s_nop 0
	v_add_f32_e32 v123, 1.0, v123
	v_rcp_f32_e32 v123, v123
	s_nop 0
	v_mul_f32_e32 v123, v123, v128
	v_cvt_pk_bf16_f32 v123, v127, v123
	global_store_dwordx4 v[124:125], v[120:123], off
	s_waitcnt lgkmcnt(0)
	s_cbranch_scc0 .LBB0_249
